# previous + the same fragment-read software pipelining inside the compiler's 256x128 MFMA blocks (gemm_in, out<4>, ffn2<4>)
# speedup vs baseline: 1.0849x; 1.0135x over previous
; #define MFMA32(a, b, c) __builtin_amdgcn_mfma_f32_32x32x16_bf16((a), (b), (c), 0, 0, 0)
; DI void gemm_kloop4(f32x16 (&acc)[4][2], const u16* __restrict__ A, int lda, const u16* __restrict__ B, int ldb, int K,
;                     char* smem) {
;     ...
;     __builtin_amdgcn_s_setprio(1);
; #pragma unroll
;     for (int s = 0; s < 4; ++s) {
;       const int ch = ((2 * s + h5) ^ sw) << 4;
;       const bf16x8 b0 = *(const bf16x8*)(smem + boff + ch);
;       const bf16x8 b1 = *(const bf16x8*)(smem + boff + 4096 + ch);
; #pragma unroll
;       for (int mt = 0; mt < 4; ++mt) {
;         const bf16x8 a = *(const bf16x8*)(smem + aoff + mt * 4096 + ch);
;         acc[mt][0] = MFMA32(a, b0, acc[mt][0]);
;         acc[mt][1] = MFMA32(a, b1, acc[mt][1]);
;       }
;     }
;     __builtin_amdgcn_s_setprio(0);
.LBB0_41:
	s_setprio 1
	v_add_u32_e32 v0, v184, v186
	ds_read_b128 v[190:193], v0 offset:32768
	ds_read_b128 v[208:211], v0 offset:36864
	v_add_u32_e32 v0, v185, v186
	ds_read_b128 v[212:215], v0
	ds_read_b128 v[248:251], v0 offset:4096
	ds_read_b128 v[252:255], v0 offset:8192
	s_waitcnt lgkmcnt(2)
	v_mfma_f32_32x32x16_bf16 v[114:129], v[212:215], v[190:193], v[114:129]
	s_waitcnt lgkmcnt(2)
	v_mfma_f32_32x32x16_bf16 v[98:113], v[212:215], v[208:211], v[98:113]
	ds_read_b128 v[212:215], v0 offset:12288
	s_waitcnt lgkmcnt(2)
	v_mfma_f32_32x32x16_bf16 v[82:97], v[248:251], v[190:193], v[82:97]
	s_waitcnt lgkmcnt(2)
	v_mfma_f32_32x32x16_bf16 v[66:81], v[248:251], v[208:211], v[66:81]
	v_add_u32_e32 v0, v184, v187
	ds_read_b128 v[248:251], v0 offset:32768
	s_waitcnt lgkmcnt(2)
	v_mfma_f32_32x32x16_bf16 v[50:65], v[252:255], v[190:193], v[50:65]
	s_waitcnt lgkmcnt(2)
	v_mfma_f32_32x32x16_bf16 v[34:49], v[252:255], v[208:211], v[34:49]
	ds_read_b128 v[252:255], v0 offset:36864
	s_waitcnt lgkmcnt(2)
	v_mfma_f32_32x32x16_bf16 v[18:33], v[212:215], v[190:193], v[18:33]
	v_add_u32_e32 v0, v185, v187
	ds_read_b128 v[190:193], v0
	s_waitcnt lgkmcnt(3)
	v_mfma_f32_32x32x16_bf16 v[2:17], v[212:215], v[208:211], v[2:17]
	ds_read_b128 v[212:215], v0 offset:4096
	ds_read_b128 v[208:211], v0 offset:8192
	s_waitcnt lgkmcnt(2)
	v_mfma_f32_32x32x16_bf16 v[114:129], v[190:193], v[248:251], v[114:129]
	s_waitcnt lgkmcnt(2)
	v_mfma_f32_32x32x16_bf16 v[98:113], v[190:193], v[252:255], v[98:113]
	ds_read_b128 v[190:193], v0 offset:12288
	s_waitcnt lgkmcnt(2)
	v_mfma_f32_32x32x16_bf16 v[82:97], v[212:215], v[248:251], v[82:97]
	s_waitcnt lgkmcnt(2)
	v_mfma_f32_32x32x16_bf16 v[66:81], v[212:215], v[252:255], v[66:81]
	v_add_u32_e32 v0, v184, v188
	ds_read_b128 v[212:215], v0 offset:32768
	s_waitcnt lgkmcnt(2)
	v_mfma_f32_32x32x16_bf16 v[50:65], v[208:211], v[248:251], v[50:65]
	s_waitcnt lgkmcnt(2)
	v_mfma_f32_32x32x16_bf16 v[34:49], v[208:211], v[252:255], v[34:49]
	ds_read_b128 v[208:211], v0 offset:36864
	s_waitcnt lgkmcnt(2)
	v_mfma_f32_32x32x16_bf16 v[18:33], v[190:193], v[248:251], v[18:33]
	v_add_u32_e32 v0, v185, v188
	ds_read_b128 v[248:251], v0
	s_waitcnt lgkmcnt(3)
	v_mfma_f32_32x32x16_bf16 v[2:17], v[190:193], v[252:255], v[2:17]
	ds_read_b128 v[190:193], v0 offset:4096
	ds_read_b128 v[252:255], v0 offset:8192
	s_waitcnt lgkmcnt(2)
	v_mfma_f32_32x32x16_bf16 v[114:129], v[248:251], v[212:215], v[114:129]
	s_waitcnt lgkmcnt(2)
	v_mfma_f32_32x32x16_bf16 v[98:113], v[248:251], v[208:211], v[98:113]
	ds_read_b128 v[248:251], v0 offset:12288
	s_waitcnt lgkmcnt(2)
	v_mfma_f32_32x32x16_bf16 v[82:97], v[190:193], v[212:215], v[82:97]
	s_waitcnt lgkmcnt(2)
	v_mfma_f32_32x32x16_bf16 v[66:81], v[190:193], v[208:211], v[66:81]
	v_add_u32_e32 v0, v184, v189
	ds_read_b128 v[190:193], v0 offset:32768
	s_waitcnt lgkmcnt(2)
	v_mfma_f32_32x32x16_bf16 v[50:65], v[252:255], v[212:215], v[50:65]
	s_waitcnt lgkmcnt(2)
	v_mfma_f32_32x32x16_bf16 v[34:49], v[252:255], v[208:211], v[34:49]
	ds_read_b128 v[252:255], v0 offset:36864
	s_waitcnt lgkmcnt(2)
	v_mfma_f32_32x32x16_bf16 v[18:33], v[248:251], v[212:215], v[18:33]
	v_add_u32_e32 v0, v185, v189
	ds_read_b128 v[212:215], v0
	s_waitcnt lgkmcnt(3)
	v_mfma_f32_32x32x16_bf16 v[2:17], v[248:251], v[208:211], v[2:17]
	ds_read_b128 v[248:251], v0 offset:4096
	ds_read_b128 v[208:211], v0 offset:8192
	s_waitcnt lgkmcnt(2)
	v_mfma_f32_32x32x16_bf16 v[114:129], v[212:215], v[190:193], v[114:129]
	s_waitcnt lgkmcnt(2)
	v_mfma_f32_32x32x16_bf16 v[98:113], v[212:215], v[252:255], v[98:113]
	ds_read_b128 v[212:215], v0 offset:12288
	s_waitcnt lgkmcnt(2)
	v_mfma_f32_32x32x16_bf16 v[82:97], v[248:251], v[190:193], v[82:97]
	s_waitcnt lgkmcnt(2)
	v_mfma_f32_32x32x16_bf16 v[66:81], v[248:251], v[252:255], v[66:81]
	s_waitcnt lgkmcnt(1)
	v_mfma_f32_32x32x16_bf16 v[50:65], v[208:211], v[190:193], v[50:65]
	s_waitcnt lgkmcnt(1)
	v_mfma_f32_32x32x16_bf16 v[34:49], v[208:211], v[252:255], v[34:49]
	s_waitcnt lgkmcnt(0)
	v_mfma_f32_32x32x16_bf16 v[18:33], v[212:215], v[190:193], v[18:33]
	s_waitcnt lgkmcnt(0)
	v_mfma_f32_32x32x16_bf16 v[2:17], v[212:215], v[252:255], v[2:17]
	s_setprio 0
	s_andn2_b64 vcc, exec, s[28:29]
	s_barrier
	s_cbranch_vccnz .LBB0_38
	s_waitcnt vmcnt(11)
	ds_write_b128 v179, v[142:145]
	s_waitcnt vmcnt(10)
	ds_write_b128 v179, v[130:133] offset:4096
	s_waitcnt vmcnt(9)
	ds_write_b128 v179, v[134:137] offset:8192
	s_waitcnt vmcnt(8)
	ds_write_b128 v179, v[138:141] offset:12288
	s_waitcnt vmcnt(7)
	ds_write_b128 v179, v[146:149] offset:16384
	s_waitcnt vmcnt(6)
	ds_write_b128 v179, v[150:153] offset:20480
	s_waitcnt vmcnt(5)
	ds_write_b128 v179, v[154:157] offset:24576
	s_waitcnt vmcnt(4)
	ds_write_b128 v179, v[158:161] offset:28672
	s_waitcnt vmcnt(3)
	ds_write_b128 v179, v[162:165] offset:32768
	s_waitcnt vmcnt(2)
	ds_write_b128 v179, v[166:169] offset:36864
	s_waitcnt vmcnt(1)
	ds_write_b128 v179, v[170:173] offset:40960
	s_waitcnt vmcnt(0)
	ds_write_b128 v179, v[174:177] offset:45056
	s_branch .LBB0_38

; #define GLOAD(RA, RB, kt_) _Pragma("unroll") for (int i = 0; i < 4; ++i) { \
;     RA[i] = *(const u32x4*)(Ap + (size_t)(32 * i) * lda + (kt_) * 64); \
;     RB[i] = *(const u32x4*)(Bp + (size_t)(32 * i) * ldb + (kt_) * 64); }
; #define LSTORE(RA, RB, buf_) _Pragma("unroll") for (int i = 0; i < 4; ++i) { \
;     *(u32x4*)(smem + (buf_) * 16384 + woff + i * 4096) = RA[i]; \
;     *(u32x4*)(smem + 32768 + (buf_) * 16384 + woff + i * 4096) = RB[i]; }
; DI void gemm_kloop(f32x16 (&acc)[2][2], const u16* __restrict__ A, int lda, const u16* __restrict__ B, int ldb, int K,
;                    char* smem) {
;     ...
;   const int woff = lr * 128 + ((lc ^ ((lr >> 1) & 7)) << 4);
;   const int sw = (r >> 1) & 7;
;   const int aoff = (wr * 64 + r) * 128, boff = 32768 + (wc * 64 + r) * 128;
;   GLOAD(ra0, rb0, 0)
;   GLOAD(ra1, rb1, 1)
;   __syncthreads();
;   LSTORE(ra0, rb0, 0)
;   __syncthreads();
; #pragma unroll 1
;   for (int kt = 0; kt < nk; kt += 2) {
;     if (kt + 2 < nk) GLOAD(ra0, rb0, kt + 2)
;     COMPUTE(0)
;     LSTORE(ra1, rb1, 1)
;     __syncthreads();
;     if (kt + 3 < nk) GLOAD(ra1, rb1, kt + 3)
;     COMPUTE(1)
;     if (kt + 2 < nk) LSTORE(ra0, rb0, 0)
;     __syncthreads();
.LBB0_52:
	s_setprio 1
	v_add_u32_e32 v145, v140, v141
	ds_read_b128 v[208:211], v145
	v_add_u32_e32 v149, v138, v141
	ds_read_b128 v[212:215], v149 offset:32768
	ds_read_b128 v[216:219], v149 offset:36864
	v_add_u32_e32 v146, v140, v142
	v_add_u32_e32 v147, v140, v143
	v_add_u32_e32 v148, v140, v144
	ds_read_b128 v[220:223], v145 offset:4096
	ds_read_b128 v[224:227], v146
	v_add_u32_e32 v150, v138, v142
	ds_read_b128 v[228:231], v150 offset:32768
	ds_read_b128 v[232:235], v150 offset:36864
	v_add_u32_e32 v151, v138, v143
	ds_read_b128 v[236:239], v146 offset:4096
	s_waitcnt lgkmcnt(6)
	v_mfma_f32_32x32x16_bf16 v[50:65], v[208:211], v[212:215], v[50:65]
	s_waitcnt lgkmcnt(5)
	v_mfma_f32_32x32x16_bf16 v[34:49], v[208:211], v[216:219], v[34:49]
	ds_read_b128 v[208:211], v151 offset:32768
	s_waitcnt lgkmcnt(5)
	v_mfma_f32_32x32x16_bf16 v[18:33], v[220:223], v[212:215], v[18:33]
	ds_read_b128 v[212:215], v147
	s_waitcnt lgkmcnt(6)
	v_mfma_f32_32x32x16_bf16 v[2:17], v[220:223], v[216:219], v[2:17]
	ds_read_b128 v[220:223], v151 offset:36864
	ds_read_b128 v[216:219], v147 offset:4096
	s_waitcnt lgkmcnt(6)
	v_mfma_f32_32x32x16_bf16 v[50:65], v[224:227], v[228:231], v[50:65]
	s_waitcnt lgkmcnt(5)
	v_mfma_f32_32x32x16_bf16 v[34:49], v[224:227], v[232:235], v[34:49]
	ds_read_b128 v[224:227], v148
	s_waitcnt lgkmcnt(5)
	v_mfma_f32_32x32x16_bf16 v[18:33], v[236:239], v[228:231], v[18:33]
	v_add_u32_e32 v152, v138, v144
	ds_read_b128 v[228:231], v152 offset:32768
	s_waitcnt lgkmcnt(6)
	v_mfma_f32_32x32x16_bf16 v[2:17], v[236:239], v[232:235], v[2:17]
	ds_read_b128 v[236:239], v152 offset:36864
	ds_read_b128 v[232:235], v148 offset:4096
	s_waitcnt lgkmcnt(6)
	v_mfma_f32_32x32x16_bf16 v[50:65], v[212:215], v[208:211], v[50:65]
	s_waitcnt lgkmcnt(5)
	v_mfma_f32_32x32x16_bf16 v[34:49], v[212:215], v[220:223], v[34:49]
	s_waitcnt lgkmcnt(4)
	v_mfma_f32_32x32x16_bf16 v[18:33], v[216:219], v[208:211], v[18:33]
	s_waitcnt lgkmcnt(4)
	v_mfma_f32_32x32x16_bf16 v[2:17], v[216:219], v[220:223], v[2:17]
	s_waitcnt lgkmcnt(2)
	v_mfma_f32_32x32x16_bf16 v[50:65], v[224:227], v[228:231], v[50:65]
	s_waitcnt lgkmcnt(1)
	v_mfma_f32_32x32x16_bf16 v[34:49], v[224:227], v[236:239], v[34:49]
	s_waitcnt lgkmcnt(0)
	v_mfma_f32_32x32x16_bf16 v[18:33], v[232:235], v[228:231], v[18:33]
	s_waitcnt lgkmcnt(0)
	v_mfma_f32_32x32x16_bf16 v[2:17], v[232:235], v[236:239], v[2:17]
	s_setprio 0
	s_cmp_gt_u32 s42, 40
	s_waitcnt vmcnt(7)
	ds_write_b128 v139, v[90:93] offset:16384
	s_waitcnt vmcnt(3)
	ds_write_b128 v139, v[98:101] offset:49152
	ds_write_b128 v139, v[102:105] offset:20480
	s_waitcnt vmcnt(2)
	ds_write_b128 v139, v[106:109] offset:53248
	ds_write_b128 v139, v[110:113] offset:24576
	s_waitcnt vmcnt(1)
	ds_write_b128 v139, v[114:117] offset:57344
	ds_write_b128 v139, v[122:125] offset:28672
	s_waitcnt vmcnt(0)
	ds_write_b128 v139, v[126:129] offset:61440
	s_waitcnt lgkmcnt(0)
	s_barrier
	s_cbranch_scc1 .LBB0_54
	v_add_co_u32_e32 v90, vcc, 0xb360000, v136
	s_nop 1
	v_addc_co_u32_e32 v91, vcc, 0, v137, vcc
	v_add_co_u32_e32 v98, vcc, 0x1dc0000, v134
	global_load_dwordx4 v[90:93], v[90:91], off offset:384
	s_nop 0
	v_addc_co_u32_e32 v99, vcc, 0, v135, vcc
	v_add_co_u32_e32 v102, vcc, 0xb38c000, v136
	global_load_dwordx4 v[98:101], v[98:99], off offset:384
	s_nop 0
	v_addc_co_u32_e32 v103, vcc, 0, v137, vcc
	v_add_co_u32_e32 v106, vcc, 0x1dec000, v134
	global_load_dwordx4 v[102:105], v[102:103], off offset:384
	s_nop 0
	v_addc_co_u32_e32 v107, vcc, 0, v135, vcc
	v_add_co_u32_e32 v110, vcc, 0xb3b8000, v136
	global_load_dwordx4 v[106:109], v[106:107], off offset:384
	s_nop 0
	v_addc_co_u32_e32 v111, vcc, 0, v137, vcc
	v_add_co_u32_e32 v114, vcc, 0x1e18000, v134
	global_load_dwordx4 v[110:113], v[110:111], off offset:384
	s_nop 0
	v_addc_co_u32_e32 v115, vcc, 0, v135, vcc
	v_add_co_u32_e32 v122, vcc, 0xb3e4000, v136
	global_load_dwordx4 v[114:117], v[114:115], off offset:384
	s_nop 0
	v_addc_co_u32_e32 v123, vcc, 0, v137, vcc
	v_add_co_u32_e32 v126, vcc, 0x1e44000, v134
	global_load_dwordx4 v[122:125], v[122:123], off offset:384
	s_nop 0
	v_addc_co_u32_e32 v127, vcc, 0, v135, vcc
	global_load_dwordx4 v[126:129], v[126:127], off offset:384

; #define MFMA32(a, b, c) __builtin_amdgcn_mfma_f32_32x32x16_bf16((a), (b), (c), 0, 0, 0)
; DI void gemm_kloop4(f32x16 (&acc)[4][2], const u16* __restrict__ A, int lda, const u16* __restrict__ B, int ldb, int K,
;                     char* smem) {
;     ...
;     __builtin_amdgcn_s_setprio(1);
; #pragma unroll
;     for (int s = 0; s < 4; ++s) {
;       const int ch = ((2 * s + h5) ^ sw) << 4;
;       const bf16x8 b0 = *(const bf16x8*)(smem + boff + ch);
;       const bf16x8 b1 = *(const bf16x8*)(smem + boff + 4096 + ch);
; #pragma unroll
;       for (int mt = 0; mt < 4; ++mt) {
;         const bf16x8 a = *(const bf16x8*)(smem + aoff + mt * 4096 + ch);
;         acc[mt][0] = MFMA32(a, b0, acc[mt][0]);
;         acc[mt][1] = MFMA32(a, b1, acc[mt][1]);
;       }
;     }
;     __builtin_amdgcn_s_setprio(0);
.LBB0_87:
	s_setprio 1
	v_add_u32_e32 v0, v184, v186
	ds_read_b128 v[190:193], v0 offset:32768
	ds_read_b128 v[208:211], v0 offset:36864
	v_add_u32_e32 v0, v185, v186
	ds_read_b128 v[212:215], v0
	ds_read_b128 v[248:251], v0 offset:4096
	ds_read_b128 v[252:255], v0 offset:8192
	s_waitcnt lgkmcnt(2)
	v_mfma_f32_32x32x16_bf16 v[114:129], v[212:215], v[190:193], v[114:129]
	s_waitcnt lgkmcnt(2)
	v_mfma_f32_32x32x16_bf16 v[98:113], v[212:215], v[208:211], v[98:113]
	ds_read_b128 v[212:215], v0 offset:12288
	s_waitcnt lgkmcnt(2)
	v_mfma_f32_32x32x16_bf16 v[82:97], v[248:251], v[190:193], v[82:97]
	s_waitcnt lgkmcnt(2)
	v_mfma_f32_32x32x16_bf16 v[66:81], v[248:251], v[208:211], v[66:81]
	v_add_u32_e32 v0, v184, v187
	ds_read_b128 v[248:251], v0 offset:32768
	s_waitcnt lgkmcnt(2)
	v_mfma_f32_32x32x16_bf16 v[50:65], v[252:255], v[190:193], v[50:65]
	s_waitcnt lgkmcnt(2)
	v_mfma_f32_32x32x16_bf16 v[34:49], v[252:255], v[208:211], v[34:49]
	ds_read_b128 v[252:255], v0 offset:36864
	s_waitcnt lgkmcnt(2)
	v_mfma_f32_32x32x16_bf16 v[18:33], v[212:215], v[190:193], v[18:33]
	v_add_u32_e32 v0, v185, v187
	ds_read_b128 v[190:193], v0
	s_waitcnt lgkmcnt(3)
	v_mfma_f32_32x32x16_bf16 v[2:17], v[212:215], v[208:211], v[2:17]
	ds_read_b128 v[212:215], v0 offset:4096
	ds_read_b128 v[208:211], v0 offset:8192
	s_waitcnt lgkmcnt(2)
	v_mfma_f32_32x32x16_bf16 v[114:129], v[190:193], v[248:251], v[114:129]
	s_waitcnt lgkmcnt(2)
	v_mfma_f32_32x32x16_bf16 v[98:113], v[190:193], v[252:255], v[98:113]
	ds_read_b128 v[190:193], v0 offset:12288
	s_waitcnt lgkmcnt(2)
	v_mfma_f32_32x32x16_bf16 v[82:97], v[212:215], v[248:251], v[82:97]
	s_waitcnt lgkmcnt(2)
	v_mfma_f32_32x32x16_bf16 v[66:81], v[212:215], v[252:255], v[66:81]
	v_add_u32_e32 v0, v184, v188
	ds_read_b128 v[212:215], v0 offset:32768
	s_waitcnt lgkmcnt(2)
	v_mfma_f32_32x32x16_bf16 v[50:65], v[208:211], v[248:251], v[50:65]
	s_waitcnt lgkmcnt(2)
	v_mfma_f32_32x32x16_bf16 v[34:49], v[208:211], v[252:255], v[34:49]
	ds_read_b128 v[208:211], v0 offset:36864
	s_waitcnt lgkmcnt(2)
	v_mfma_f32_32x32x16_bf16 v[18:33], v[190:193], v[248:251], v[18:33]
	v_add_u32_e32 v0, v185, v188
	ds_read_b128 v[248:251], v0
	s_waitcnt lgkmcnt(3)
	v_mfma_f32_32x32x16_bf16 v[2:17], v[190:193], v[252:255], v[2:17]
	ds_read_b128 v[190:193], v0 offset:4096
	ds_read_b128 v[252:255], v0 offset:8192
	s_waitcnt lgkmcnt(2)
	v_mfma_f32_32x32x16_bf16 v[114:129], v[248:251], v[212:215], v[114:129]
	s_waitcnt lgkmcnt(2)
	v_mfma_f32_32x32x16_bf16 v[98:113], v[248:251], v[208:211], v[98:113]
	ds_read_b128 v[248:251], v0 offset:12288
	s_waitcnt lgkmcnt(2)
	v_mfma_f32_32x32x16_bf16 v[82:97], v[190:193], v[212:215], v[82:97]
	s_waitcnt lgkmcnt(2)
	v_mfma_f32_32x32x16_bf16 v[66:81], v[190:193], v[208:211], v[66:81]
	v_add_u32_e32 v0, v184, v189
	ds_read_b128 v[190:193], v0 offset:32768
	s_waitcnt lgkmcnt(2)
	v_mfma_f32_32x32x16_bf16 v[50:65], v[252:255], v[212:215], v[50:65]
	s_waitcnt lgkmcnt(2)
	v_mfma_f32_32x32x16_bf16 v[34:49], v[252:255], v[208:211], v[34:49]
	ds_read_b128 v[252:255], v0 offset:36864
	s_waitcnt lgkmcnt(2)
	v_mfma_f32_32x32x16_bf16 v[18:33], v[248:251], v[212:215], v[18:33]
	v_add_u32_e32 v0, v185, v189
	ds_read_b128 v[212:215], v0
	s_waitcnt lgkmcnt(3)
	v_mfma_f32_32x32x16_bf16 v[2:17], v[248:251], v[208:211], v[2:17]
	ds_read_b128 v[248:251], v0 offset:4096
	ds_read_b128 v[208:211], v0 offset:8192
	s_waitcnt lgkmcnt(2)
	v_mfma_f32_32x32x16_bf16 v[114:129], v[212:215], v[190:193], v[114:129]
	s_waitcnt lgkmcnt(2)
	v_mfma_f32_32x32x16_bf16 v[98:113], v[212:215], v[252:255], v[98:113]
	ds_read_b128 v[212:215], v0 offset:12288
	s_waitcnt lgkmcnt(2)
	v_mfma_f32_32x32x16_bf16 v[82:97], v[248:251], v[190:193], v[82:97]
	s_waitcnt lgkmcnt(2)
	v_mfma_f32_32x32x16_bf16 v[66:81], v[248:251], v[252:255], v[66:81]
	s_waitcnt lgkmcnt(1)
	v_mfma_f32_32x32x16_bf16 v[50:65], v[208:211], v[190:193], v[50:65]
	s_waitcnt lgkmcnt(1)
	v_mfma_f32_32x32x16_bf16 v[34:49], v[208:211], v[252:255], v[34:49]
	s_waitcnt lgkmcnt(0)
	v_mfma_f32_32x32x16_bf16 v[18:33], v[212:215], v[190:193], v[18:33]
	s_waitcnt lgkmcnt(0)
	v_mfma_f32_32x32x16_bf16 v[2:17], v[212:215], v[252:255], v[2:17]
	s_setprio 0
	s_andn2_b64 vcc, exec, s[38:39]
	s_barrier
	s_cbranch_vccnz .LBB0_84
	s_waitcnt vmcnt(11)
	ds_write_b128 v179, v[142:145]
	s_waitcnt vmcnt(10)
	ds_write_b128 v179, v[130:133] offset:4096
	s_waitcnt vmcnt(9)
	ds_write_b128 v179, v[134:137] offset:8192
	s_waitcnt vmcnt(8)
	ds_write_b128 v179, v[138:141] offset:12288
	s_waitcnt vmcnt(7)
	ds_write_b128 v179, v[146:149] offset:16384
	s_waitcnt vmcnt(6)
	ds_write_b128 v179, v[150:153] offset:20480
	s_waitcnt vmcnt(5)
	ds_write_b128 v179, v[154:157] offset:24576
	s_waitcnt vmcnt(4)
	ds_write_b128 v179, v[158:161] offset:28672
	s_waitcnt vmcnt(3)
	ds_write_b128 v179, v[162:165] offset:32768
	s_waitcnt vmcnt(2)
	ds_write_b128 v179, v[166:169] offset:36864
	s_waitcnt vmcnt(1)
	ds_write_b128 v179, v[170:173] offset:40960
	s_waitcnt vmcnt(0)
	ds_write_b128 v179, v[174:177] offset:45056
	s_branch .LBB0_84

; #define GLOAD(RA, RB, kt_) _Pragma("unroll") for (int i = 0; i < 4; ++i) { \
;     RA[i] = *(const u32x4*)(Ap + (size_t)(32 * i) * lda + (kt_) * 64); \
;     RB[i] = *(const u32x4*)(Bp + (size_t)(32 * i) * ldb + (kt_) * 64); }
; #define LSTORE(RA, RB, buf_) _Pragma("unroll") for (int i = 0; i < 4; ++i) { \
;     *(u32x4*)(smem + (buf_) * 16384 + woff + i * 4096) = RA[i]; \
;     *(u32x4*)(smem + 32768 + (buf_) * 16384 + woff + i * 4096) = RB[i]; }
; DI void gemm_kloop(f32x16 (&acc)[2][2], const u16* __restrict__ A, int lda, const u16* __restrict__ B, int ldb, int K,
;                    char* smem) {
;     ...
;   const int woff = lr * 128 + ((lc ^ ((lr >> 1) & 7)) << 4);
;   const int sw = (r >> 1) & 7;
;   const int aoff = (wr * 64 + r) * 128, boff = 32768 + (wc * 64 + r) * 128;
;   GLOAD(ra0, rb0, 0)
;   GLOAD(ra1, rb1, 1)
;   __syncthreads();
;   LSTORE(ra0, rb0, 0)
;   __syncthreads();
; #pragma unroll 1
;   for (int kt = 0; kt < nk; kt += 2) {
;     if (kt + 2 < nk) GLOAD(ra0, rb0, kt + 2)
;     COMPUTE(0)
;     LSTORE(ra1, rb1, 1)
;     __syncthreads();
;     if (kt + 3 < nk) GLOAD(ra1, rb1, kt + 3)
;     COMPUTE(1)
;     if (kt + 2 < nk) LSTORE(ra0, rb0, 0)
;     __syncthreads();
.LBB0_98:
	s_setprio 1
	v_add_u32_e32 v145, v140, v141
	ds_read_b128 v[208:211], v145
	v_add_u32_e32 v149, v138, v141
	ds_read_b128 v[212:215], v149 offset:32768
	ds_read_b128 v[216:219], v149 offset:36864
	v_add_u32_e32 v146, v140, v142
	v_add_u32_e32 v147, v140, v143
	v_add_u32_e32 v148, v140, v144
	ds_read_b128 v[220:223], v145 offset:4096
	ds_read_b128 v[224:227], v146
	v_add_u32_e32 v150, v138, v142
	ds_read_b128 v[228:231], v150 offset:32768
	ds_read_b128 v[232:235], v150 offset:36864
	v_add_u32_e32 v151, v138, v143
	ds_read_b128 v[236:239], v146 offset:4096
	s_waitcnt lgkmcnt(6)
	v_mfma_f32_32x32x16_bf16 v[50:65], v[208:211], v[212:215], v[50:65]
	s_waitcnt lgkmcnt(5)
	v_mfma_f32_32x32x16_bf16 v[34:49], v[208:211], v[216:219], v[34:49]
	ds_read_b128 v[208:211], v151 offset:32768
	s_waitcnt lgkmcnt(5)
	v_mfma_f32_32x32x16_bf16 v[18:33], v[220:223], v[212:215], v[18:33]
	ds_read_b128 v[212:215], v147
	s_waitcnt lgkmcnt(6)
	v_mfma_f32_32x32x16_bf16 v[2:17], v[220:223], v[216:219], v[2:17]
	ds_read_b128 v[220:223], v151 offset:36864
	ds_read_b128 v[216:219], v147 offset:4096
	s_waitcnt lgkmcnt(6)
	v_mfma_f32_32x32x16_bf16 v[50:65], v[224:227], v[228:231], v[50:65]
	s_waitcnt lgkmcnt(5)
	v_mfma_f32_32x32x16_bf16 v[34:49], v[224:227], v[232:235], v[34:49]
	ds_read_b128 v[224:227], v148
	s_waitcnt lgkmcnt(5)
	v_mfma_f32_32x32x16_bf16 v[18:33], v[236:239], v[228:231], v[18:33]
	v_add_u32_e32 v152, v138, v144
	ds_read_b128 v[228:231], v152 offset:32768
	s_waitcnt lgkmcnt(6)
	v_mfma_f32_32x32x16_bf16 v[2:17], v[236:239], v[232:235], v[2:17]
	ds_read_b128 v[236:239], v152 offset:36864
	ds_read_b128 v[232:235], v148 offset:4096
	s_waitcnt lgkmcnt(6)
	v_mfma_f32_32x32x16_bf16 v[50:65], v[212:215], v[208:211], v[50:65]
	s_waitcnt lgkmcnt(5)
	v_mfma_f32_32x32x16_bf16 v[34:49], v[212:215], v[220:223], v[34:49]
	s_waitcnt lgkmcnt(4)
	v_mfma_f32_32x32x16_bf16 v[18:33], v[216:219], v[208:211], v[18:33]
	s_waitcnt lgkmcnt(4)
	v_mfma_f32_32x32x16_bf16 v[2:17], v[216:219], v[220:223], v[2:17]
	s_waitcnt lgkmcnt(2)
	v_mfma_f32_32x32x16_bf16 v[50:65], v[224:227], v[228:231], v[50:65]
	s_waitcnt lgkmcnt(1)
	v_mfma_f32_32x32x16_bf16 v[34:49], v[224:227], v[236:239], v[34:49]
	s_waitcnt lgkmcnt(0)
	v_mfma_f32_32x32x16_bf16 v[18:33], v[232:235], v[228:231], v[18:33]
	s_waitcnt lgkmcnt(0)
	v_mfma_f32_32x32x16_bf16 v[2:17], v[232:235], v[236:239], v[2:17]
	s_setprio 0
	s_cmp_gt_u32 s1, 12
	s_waitcnt vmcnt(7)
	ds_write_b128 v139, v[90:93] offset:16384
	s_waitcnt vmcnt(3)
	ds_write_b128 v139, v[98:101] offset:49152
	ds_write_b128 v139, v[102:105] offset:20480
	s_waitcnt vmcnt(2)
	ds_write_b128 v139, v[106:109] offset:53248
	ds_write_b128 v139, v[110:113] offset:24576
	s_waitcnt vmcnt(1)
	ds_write_b128 v139, v[114:117] offset:57344
	ds_write_b128 v139, v[122:125] offset:28672
	s_waitcnt vmcnt(0)
	ds_write_b128 v139, v[126:129] offset:61440
	s_waitcnt lgkmcnt(0)
	s_barrier
	s_cbranch_scc1 .LBB0_100
	v_add_co_u32_e32 v90, vcc, 0x6b60000, v136
	s_nop 1
	v_addc_co_u32_e32 v91, vcc, 0, v137, vcc
	v_add_co_u32_e32 v98, vcc, 0x10c0000, v134
	global_load_dwordx4 v[90:93], v[90:91], off offset:384
	s_nop 0
	v_addc_co_u32_e32 v99, vcc, 0, v135, vcc
	v_add_co_u32_e32 v102, vcc, 0x6b70000, v136
	global_load_dwordx4 v[98:101], v[98:99], off offset:384
	s_nop 0
	v_addc_co_u32_e32 v103, vcc, 0, v137, vcc
	v_add_co_u32_e32 v106, vcc, 0x10d0000, v134
	global_load_dwordx4 v[102:105], v[102:103], off offset:384
	s_nop 0
	v_addc_co_u32_e32 v107, vcc, 0, v135, vcc
	v_add_co_u32_e32 v110, vcc, 0x6b80000, v136
	global_load_dwordx4 v[106:109], v[106:107], off offset:384
	s_nop 0
	v_addc_co_u32_e32 v111, vcc, 0, v137, vcc
	v_add_co_u32_e32 v114, vcc, 0x10e0000, v134
	global_load_dwordx4 v[110:113], v[110:111], off offset:384
	s_nop 0
	v_addc_co_u32_e32 v115, vcc, 0, v135, vcc
	v_add_co_u32_e32 v122, vcc, 0x6b90000, v136
	global_load_dwordx4 v[114:117], v[114:115], off offset:384
	s_nop 0
	v_addc_co_u32_e32 v123, vcc, 0, v137, vcc
	v_add_co_u32_e32 v126, vcc, 0x10f0000, v134
	global_load_dwordx4 v[122:125], v[122:123], off offset:384
	s_nop 0
	v_addc_co_u32_e32 v127, vcc, 0, v135, vcc
	global_load_dwordx4 v[126:129], v[126:127], off offset:384

; #define GLOAD(RA, RB, kt_) _Pragma("unroll") for (int i = 0; i < 4; ++i) { \
;     RA[i] = *(const u32x4*)(Ap + (size_t)(32 * i) * lda + (kt_) * 64); \
;     RB[i] = *(const u32x4*)(Bp + (size_t)(32 * i) * ldb + (kt_) * 64); }
; #define LSTORE(RA, RB, buf_) _Pragma("unroll") for (int i = 0; i < 4; ++i) { \
;     *(u32x4*)(smem + (buf_) * 16384 + woff + i * 4096) = RA[i]; \
;     *(u32x4*)(smem + 32768 + (buf_) * 16384 + woff + i * 4096) = RB[i]; }
; DI void gemm_kloop(f32x16 (&acc)[2][2], const u16* __restrict__ A, int lda, const u16* __restrict__ B, int ldb, int K,
;                    char* smem) {
;     ...
;   const int woff = lr * 128 + ((lc ^ ((lr >> 1) & 7)) << 4);
;   const int sw = (r >> 1) & 7;
;   const int aoff = (wr * 64 + r) * 128, boff = 32768 + (wc * 64 + r) * 128;
;   GLOAD(ra0, rb0, 0)
;   GLOAD(ra1, rb1, 1)
;   __syncthreads();
;   LSTORE(ra0, rb0, 0)
;   __syncthreads();
; #pragma unroll 1
;   for (int kt = 0; kt < nk; kt += 2) {
;     if (kt + 2 < nk) GLOAD(ra0, rb0, kt + 2)
;     COMPUTE(0)
;     LSTORE(ra1, rb1, 1)
;     __syncthreads();
;     if (kt + 3 < nk) GLOAD(ra1, rb1, kt + 3)
;     COMPUTE(1)
;     if (kt + 2 < nk) LSTORE(ra0, rb0, 0)
;     __syncthreads();
; DI void gemm_merge_phase(const Params& p, int mrows, int bid, int nb, char* smem) {
;     ...
;     gemm_kloop(a, H + (size_t)row0 * 1024, 1024, WT + WT_IN + (size_t)(NIN + col0) * 1024, 1024, 1024, smem);
.LBB0_112:
	s_setprio 1
	v_add_u32_e32 v145, v140, v141
	ds_read_b128 v[208:211], v145
	v_add_u32_e32 v149, v139, v141
	ds_read_b128 v[212:215], v149 offset:32768
	ds_read_b128 v[216:219], v149 offset:36864
	v_add_u32_e32 v146, v140, v142
	v_add_u32_e32 v147, v140, v143
	v_add_u32_e32 v148, v140, v144
	ds_read_b128 v[220:223], v145 offset:4096
	ds_read_b128 v[224:227], v146
	v_add_u32_e32 v150, v139, v142
	ds_read_b128 v[228:231], v150 offset:32768
	ds_read_b128 v[232:235], v150 offset:36864
	v_add_u32_e32 v151, v139, v143
	ds_read_b128 v[236:239], v146 offset:4096
	s_waitcnt lgkmcnt(6)
	v_mfma_f32_32x32x16_bf16 v[50:65], v[208:211], v[212:215], v[50:65]
	s_waitcnt lgkmcnt(5)
	v_mfma_f32_32x32x16_bf16 v[34:49], v[208:211], v[216:219], v[34:49]
	ds_read_b128 v[208:211], v151 offset:32768
	s_waitcnt lgkmcnt(5)
	v_mfma_f32_32x32x16_bf16 v[18:33], v[220:223], v[212:215], v[18:33]
	ds_read_b128 v[212:215], v147
	s_waitcnt lgkmcnt(6)
	v_mfma_f32_32x32x16_bf16 v[2:17], v[220:223], v[216:219], v[2:17]
	ds_read_b128 v[220:223], v151 offset:36864
	ds_read_b128 v[216:219], v147 offset:4096
	s_waitcnt lgkmcnt(6)
	v_mfma_f32_32x32x16_bf16 v[50:65], v[224:227], v[228:231], v[50:65]
	s_waitcnt lgkmcnt(5)
	v_mfma_f32_32x32x16_bf16 v[34:49], v[224:227], v[232:235], v[34:49]
	ds_read_b128 v[224:227], v148
	s_waitcnt lgkmcnt(5)
	v_mfma_f32_32x32x16_bf16 v[18:33], v[236:239], v[228:231], v[18:33]
	v_add_u32_e32 v152, v139, v144
	ds_read_b128 v[228:231], v152 offset:32768
	s_waitcnt lgkmcnt(6)
	v_mfma_f32_32x32x16_bf16 v[2:17], v[236:239], v[232:235], v[2:17]
	ds_read_b128 v[236:239], v152 offset:36864
	ds_read_b128 v[232:235], v148 offset:4096
	s_waitcnt lgkmcnt(6)
	v_mfma_f32_32x32x16_bf16 v[50:65], v[212:215], v[208:211], v[50:65]
	s_waitcnt lgkmcnt(5)
	v_mfma_f32_32x32x16_bf16 v[34:49], v[212:215], v[220:223], v[34:49]
	s_waitcnt lgkmcnt(4)
	v_mfma_f32_32x32x16_bf16 v[18:33], v[216:219], v[208:211], v[18:33]
	s_waitcnt lgkmcnt(4)
	v_mfma_f32_32x32x16_bf16 v[2:17], v[216:219], v[220:223], v[2:17]
	s_waitcnt lgkmcnt(2)
	v_mfma_f32_32x32x16_bf16 v[50:65], v[224:227], v[228:231], v[50:65]
	s_waitcnt lgkmcnt(1)
	v_mfma_f32_32x32x16_bf16 v[34:49], v[224:227], v[236:239], v[34:49]
	s_waitcnt lgkmcnt(0)
	v_mfma_f32_32x32x16_bf16 v[18:33], v[232:235], v[228:231], v[18:33]
	s_waitcnt lgkmcnt(0)
	v_mfma_f32_32x32x16_bf16 v[2:17], v[232:235], v[236:239], v[2:17]
	s_setprio 0
	s_cmp_gt_u32 s29, 12
	s_waitcnt vmcnt(7)
	ds_write_b128 v138, v[82:85] offset:16384
	s_waitcnt vmcnt(3)
	ds_write_b128 v138, v[90:93] offset:49152
	ds_write_b128 v138, v[98:101] offset:20480
	s_waitcnt vmcnt(2)
	ds_write_b128 v138, v[106:109] offset:53248
	ds_write_b128 v138, v[110:113] offset:24576
	s_waitcnt vmcnt(1)
	ds_write_b128 v138, v[114:117] offset:57344
	ds_write_b128 v138, v[118:121] offset:28672
	s_waitcnt vmcnt(0)
	ds_write_b128 v138, v[122:125] offset:61440
	s_waitcnt lgkmcnt(0)
	s_barrier
	s_cbranch_scc1 .LBB0_114
	v_add_co_u32_e32 v82, vcc, 0x2360000, v136
	s_nop 1
	v_addc_co_u32_e32 v83, vcc, 0, v137, vcc
	v_add_co_u32_e32 v90, vcc, 0x9c0000, v134
	global_load_dwordx4 v[82:85], v[82:83], off offset:384
	s_nop 0
	v_addc_co_u32_e32 v91, vcc, 0, v135, vcc
	v_add_co_u32_e32 v98, vcc, 0x2370000, v136
	global_load_dwordx4 v[90:93], v[90:91], off offset:384
	s_nop 0
	v_addc_co_u32_e32 v99, vcc, 0, v137, vcc
	v_add_co_u32_e32 v106, vcc, 0x9d0000, v134
	global_load_dwordx4 v[98:101], v[98:99], off offset:384
	s_nop 0
	v_addc_co_u32_e32 v107, vcc, 0, v135, vcc
	v_add_co_u32_e32 v110, vcc, 0x2380000, v136
	global_load_dwordx4 v[106:109], v[106:107], off offset:384
	s_nop 0
	v_addc_co_u32_e32 v111, vcc, 0, v137, vcc
	v_add_co_u32_e32 v114, vcc, 0x9e0000, v134
	global_load_dwordx4 v[110:113], v[110:111], off offset:384
	s_nop 0
	v_addc_co_u32_e32 v115, vcc, 0, v135, vcc
	v_add_co_u32_e32 v118, vcc, 0x2390000, v136
	global_load_dwordx4 v[114:117], v[114:115], off offset:384
	s_nop 0
	v_addc_co_u32_e32 v119, vcc, 0, v137, vcc
	v_add_co_u32_e32 v122, vcc, 0x9f0000, v134
	global_load_dwordx4 v[118:121], v[118:119], off offset:384
	s_nop 0
	v_addc_co_u32_e32 v123, vcc, 0, v135, vcc
	global_load_dwordx4 v[122:125], v[122:123], off offset:384

; #define GLOAD(RA, RB, kt_) _Pragma("unroll") for (int i = 0; i < 4; ++i) { \
;     RA[i] = *(const u32x4*)(Ap + (size_t)(32 * i) * lda + (kt_) * 64); \
;     RB[i] = *(const u32x4*)(Bp + (size_t)(32 * i) * ldb + (kt_) * 64); }
; #define LSTORE(RA, RB, buf_) _Pragma("unroll") for (int i = 0; i < 4; ++i) { \
;     *(u32x4*)(smem + (buf_) * 16384 + woff + i * 4096) = RA[i]; \
;     *(u32x4*)(smem + 32768 + (buf_) * 16384 + woff + i * 4096) = RB[i]; }
; DI void gemm_kloop(f32x16 (&acc)[2][2], const u16* __restrict__ A, int lda, const u16* __restrict__ B, int ldb, int K,
;                    char* smem) {
;     ...
;   const int woff = lr * 128 + ((lc ^ ((lr >> 1) & 7)) << 4);
;   const int sw = (r >> 1) & 7;
;   const int aoff = (wr * 64 + r) * 128, boff = 32768 + (wc * 64 + r) * 128;
;   GLOAD(ra0, rb0, 0)
;   GLOAD(ra1, rb1, 1)
;   __syncthreads();
;   LSTORE(ra0, rb0, 0)
;   __syncthreads();
; #pragma unroll 1
;   for (int kt = 0; kt < nk; kt += 2) {
;     if (kt + 2 < nk) GLOAD(ra0, rb0, kt + 2)
;     COMPUTE(0)
;     LSTORE(ra1, rb1, 1)
;     __syncthreads();
;     if (kt + 3 < nk) GLOAD(ra1, rb1, kt + 3)
;     COMPUTE(1)
;     if (kt + 2 < nk) LSTORE(ra0, rb0, 0)
;     __syncthreads();
; DI void gemm_merge_phase(const Params& p, int mrows, int bid, int nb, char* smem) {
;     ...
;     gemm_kloop(a, YRET + (size_t)row0 * 1024, 1024, WT + WT_A + (size_t)col0 * 1024, 1024, 1024, smem);
.LBB0_120:
	s_setprio 1
	v_add_u32_e32 v221, v216, v217
	ds_read_b128 v[230:233], v221
	v_add_u32_e32 v225, v215, v217
	ds_read_b128 v[234:237], v225 offset:32768
	ds_read_b128 v[238:241], v225 offset:36864
	v_add_u32_e32 v222, v216, v218
	v_add_u32_e32 v223, v216, v219
	v_add_u32_e32 v224, v216, v220
	ds_read_b128 v[248:251], v221 offset:4096
	ds_read_b128 v[252:255], v222
	s_waitcnt lgkmcnt(3)
	v_mfma_f32_32x32x16_bf16 v[50:65], v[230:233], v[234:237], v[50:65]
	s_waitcnt lgkmcnt(2)
	v_mfma_f32_32x32x16_bf16 v[34:49], v[230:233], v[238:241], v[34:49]
	v_add_u32_e32 v226, v215, v218
	ds_read_b128 v[230:233], v226 offset:32768
	s_waitcnt lgkmcnt(2)
	v_mfma_f32_32x32x16_bf16 v[18:33], v[248:251], v[234:237], v[18:33]
	ds_read_b128 v[234:237], v226 offset:36864
	s_waitcnt lgkmcnt(3)
	v_mfma_f32_32x32x16_bf16 v[2:17], v[248:251], v[238:241], v[2:17]
	v_add_u32_e32 v227, v215, v219
	ds_read_b128 v[248:251], v222 offset:4096
	ds_read_b128 v[238:241], v227 offset:32768
	s_waitcnt lgkmcnt(3)
	v_mfma_f32_32x32x16_bf16 v[50:65], v[252:255], v[230:233], v[50:65]
	s_waitcnt lgkmcnt(2)
	v_mfma_f32_32x32x16_bf16 v[34:49], v[252:255], v[234:237], v[34:49]
	ds_read_b128 v[252:255], v223
	s_waitcnt lgkmcnt(2)
	v_mfma_f32_32x32x16_bf16 v[18:33], v[248:251], v[230:233], v[18:33]
	ds_read_b128 v[230:233], v227 offset:36864
	s_waitcnt lgkmcnt(3)
	v_mfma_f32_32x32x16_bf16 v[2:17], v[248:251], v[234:237], v[2:17]
	ds_read_b128 v[248:251], v223 offset:4096
	ds_read_b128 v[234:237], v224
	s_waitcnt lgkmcnt(3)
	v_mfma_f32_32x32x16_bf16 v[50:65], v[252:255], v[238:241], v[50:65]
	s_waitcnt lgkmcnt(2)
	v_mfma_f32_32x32x16_bf16 v[34:49], v[252:255], v[230:233], v[34:49]
	v_add_u32_e32 v228, v215, v220
	ds_read_b128 v[252:255], v228 offset:32768
	s_waitcnt lgkmcnt(2)
	v_mfma_f32_32x32x16_bf16 v[18:33], v[248:251], v[238:241], v[18:33]
	ds_read_b128 v[238:241], v228 offset:36864
	s_waitcnt lgkmcnt(3)
	v_mfma_f32_32x32x16_bf16 v[2:17], v[248:251], v[230:233], v[2:17]
	ds_read_b128 v[248:251], v224 offset:4096
	s_waitcnt lgkmcnt(2)
	v_mfma_f32_32x32x16_bf16 v[50:65], v[234:237], v[252:255], v[50:65]
	s_waitcnt lgkmcnt(1)
	v_mfma_f32_32x32x16_bf16 v[34:49], v[234:237], v[238:241], v[34:49]
	s_waitcnt lgkmcnt(0)
	v_mfma_f32_32x32x16_bf16 v[18:33], v[248:251], v[252:255], v[18:33]
	s_waitcnt lgkmcnt(0)
	v_mfma_f32_32x32x16_bf16 v[2:17], v[248:251], v[238:241], v[2:17]
	s_setprio 0
	s_cmp_gt_u32 s9, 12
	s_waitcnt vmcnt(7)
	ds_write_b128 v214, v[94:97] offset:16384
	s_waitcnt vmcnt(6)
	ds_write_b128 v214, v[98:101] offset:49152
	s_waitcnt vmcnt(5)
	ds_write_b128 v214, v[102:105] offset:20480
	s_waitcnt vmcnt(4)
	ds_write_b128 v214, v[106:109] offset:53248
	s_waitcnt vmcnt(3)
	ds_write_b128 v214, v[114:117] offset:24576
	s_waitcnt vmcnt(2)
	ds_write_b128 v214, v[118:121] offset:57344
	s_waitcnt vmcnt(1)
	ds_write_b128 v214, v[122:125] offset:28672
	s_waitcnt vmcnt(0)
	ds_write_b128 v214, v[126:129] offset:61440
	s_waitcnt lgkmcnt(0)
	s_barrier
	s_cbranch_scc1 .LBB0_122
	v_add_co_u32_e32 v94, vcc, 0xfb60000, v136
	s_nop 1
	v_addc_co_u32_e32 v95, vcc, 0, v137, vcc
	v_add_co_u32_e32 v98, vcc, 0xdc0000, v134
	global_load_dwordx4 v[94:97], v[94:95], off offset:384
	s_nop 0
	v_addc_co_u32_e32 v99, vcc, 0, v135, vcc
	v_add_co_u32_e32 v102, vcc, 0xfb70000, v136
	global_load_dwordx4 v[98:101], v[98:99], off offset:384
	s_nop 0
	v_addc_co_u32_e32 v103, vcc, 0, v137, vcc
	v_add_co_u32_e32 v106, vcc, 0xdd0000, v134
	global_load_dwordx4 v[102:105], v[102:103], off offset:384
	s_nop 0
	v_addc_co_u32_e32 v107, vcc, 0, v135, vcc
	v_add_co_u32_e32 v114, vcc, 0xfb80000, v136
	global_load_dwordx4 v[106:109], v[106:107], off offset:384
	s_nop 0
	v_addc_co_u32_e32 v115, vcc, 0, v137, vcc
	v_add_co_u32_e32 v118, vcc, 0xde0000, v134
	global_load_dwordx4 v[114:117], v[114:115], off offset:384
	s_nop 0
	v_addc_co_u32_e32 v119, vcc, 0, v135, vcc
	v_add_co_u32_e32 v122, vcc, 0xfb90000, v136
	global_load_dwordx4 v[118:121], v[118:119], off offset:384
	s_nop 0
	v_addc_co_u32_e32 v123, vcc, 0, v137, vcc
	v_add_co_u32_e32 v126, vcc, 0xdf0000, v134
	global_load_dwordx4 v[122:125], v[122:123], off offset:384
	s_nop 0
	v_addc_co_u32_e32 v127, vcc, 0, v135, vcc
	global_load_dwordx4 v[126:129], v[126:127], off offset:384

; #define GLOAD(RA, RB, kt_) _Pragma("unroll") for (int i = 0; i < 4; ++i) { \
;     RA[i] = *(const u32x4*)(Ap + (size_t)(32 * i) * lda + (kt_) * 64); \
;     RB[i] = *(const u32x4*)(Bp + (size_t)(32 * i) * ldb + (kt_) * 64); }
; #define LSTORE(RA, RB, buf_) _Pragma("unroll") for (int i = 0; i < 4; ++i) { \
;     *(u32x4*)(smem + (buf_) * 16384 + woff + i * 4096) = RA[i]; \
;     *(u32x4*)(smem + 32768 + (buf_) * 16384 + woff + i * 4096) = RB[i]; }
; DI void gemm_kloop(f32x16 (&acc)[2][2], const u16* __restrict__ A, int lda, const u16* __restrict__ B, int ldb, int K,
;                    char* smem) {
;     ...
;   const int woff = lr * 128 + ((lc ^ ((lr >> 1) & 7)) << 4);
;   const int sw = (r >> 1) & 7;
;   const int aoff = (wr * 64 + r) * 128, boff = 32768 + (wc * 64 + r) * 128;
;   GLOAD(ra0, rb0, 0)
;   GLOAD(ra1, rb1, 1)
;   __syncthreads();
;   LSTORE(ra0, rb0, 0)
;   __syncthreads();
; #pragma unroll 1
;   for (int kt = 0; kt < nk; kt += 2) {
;     if (kt + 2 < nk) GLOAD(ra0, rb0, kt + 2)
;     COMPUTE(0)
;     LSTORE(ra1, rb1, 1)
;     __syncthreads();
;     if (kt + 3 < nk) GLOAD(ra1, rb1, kt + 3)
;     COMPUTE(1)
;     if (kt + 2 < nk) LSTORE(ra0, rb0, 0)
;     __syncthreads();
; DI void gemm_merge_phase(const Params& p, int mrows, int bid, int nb, char* smem) {
;     ...
;     gemm_kloop(a, H + (size_t)row0 * 1024, 1024, WT + WT_IN + (size_t)(NIN + 1024 + col0) * 1024, 1024, 1024, smem);
.LBB0_128:
	s_setprio 1
	v_add_u32_e32 v145, v140, v141
	ds_read_b128 v[208:211], v145
	v_add_u32_e32 v149, v139, v141
	ds_read_b128 v[212:215], v149 offset:32768
	ds_read_b128 v[216:219], v149 offset:36864
	v_add_u32_e32 v146, v140, v142
	v_add_u32_e32 v147, v140, v143
	v_add_u32_e32 v148, v140, v144
	ds_read_b128 v[220:223], v145 offset:4096
	ds_read_b128 v[224:227], v146
	v_add_u32_e32 v150, v139, v142
	ds_read_b128 v[228:231], v150 offset:32768
	ds_read_b128 v[232:235], v150 offset:36864
	v_add_u32_e32 v151, v139, v143
	ds_read_b128 v[236:239], v146 offset:4096
	s_waitcnt lgkmcnt(6)
	v_mfma_f32_32x32x16_bf16 v[50:65], v[208:211], v[212:215], v[50:65]
	s_waitcnt lgkmcnt(5)
	v_mfma_f32_32x32x16_bf16 v[34:49], v[208:211], v[216:219], v[34:49]
	ds_read_b128 v[208:211], v151 offset:32768
	s_waitcnt lgkmcnt(5)
	v_mfma_f32_32x32x16_bf16 v[18:33], v[220:223], v[212:215], v[18:33]
	ds_read_b128 v[212:215], v147
	s_waitcnt lgkmcnt(6)
	v_mfma_f32_32x32x16_bf16 v[2:17], v[220:223], v[216:219], v[2:17]
	ds_read_b128 v[220:223], v151 offset:36864
	ds_read_b128 v[216:219], v147 offset:4096
	s_waitcnt lgkmcnt(6)
	v_mfma_f32_32x32x16_bf16 v[50:65], v[224:227], v[228:231], v[50:65]
	s_waitcnt lgkmcnt(5)
	v_mfma_f32_32x32x16_bf16 v[34:49], v[224:227], v[232:235], v[34:49]
	ds_read_b128 v[224:227], v148
	s_waitcnt lgkmcnt(5)
	v_mfma_f32_32x32x16_bf16 v[18:33], v[236:239], v[228:231], v[18:33]
	v_add_u32_e32 v152, v139, v144
	ds_read_b128 v[228:231], v152 offset:32768
	s_waitcnt lgkmcnt(6)
	v_mfma_f32_32x32x16_bf16 v[2:17], v[236:239], v[232:235], v[2:17]
	ds_read_b128 v[236:239], v152 offset:36864
	ds_read_b128 v[232:235], v148 offset:4096
	s_waitcnt lgkmcnt(6)
	v_mfma_f32_32x32x16_bf16 v[50:65], v[212:215], v[208:211], v[50:65]
	s_waitcnt lgkmcnt(5)
	v_mfma_f32_32x32x16_bf16 v[34:49], v[212:215], v[220:223], v[34:49]
	s_waitcnt lgkmcnt(4)
	v_mfma_f32_32x32x16_bf16 v[18:33], v[216:219], v[208:211], v[18:33]
	s_waitcnt lgkmcnt(4)
	v_mfma_f32_32x32x16_bf16 v[2:17], v[216:219], v[220:223], v[2:17]
	s_waitcnt lgkmcnt(2)
	v_mfma_f32_32x32x16_bf16 v[50:65], v[224:227], v[228:231], v[50:65]
	s_waitcnt lgkmcnt(1)
	v_mfma_f32_32x32x16_bf16 v[34:49], v[224:227], v[236:239], v[34:49]
	s_waitcnt lgkmcnt(0)
	v_mfma_f32_32x32x16_bf16 v[18:33], v[232:235], v[228:231], v[18:33]
	s_waitcnt lgkmcnt(0)
	v_mfma_f32_32x32x16_bf16 v[2:17], v[232:235], v[236:239], v[2:17]
	s_setprio 0
	s_cmp_gt_u32 s9, 12
	s_waitcnt vmcnt(7)
	ds_write_b128 v138, v[82:85] offset:16384
	s_waitcnt vmcnt(6)
	ds_write_b128 v138, v[86:89] offset:49152
	s_waitcnt vmcnt(5)
	ds_write_b128 v138, v[94:97] offset:20480
	s_waitcnt vmcnt(4)
	ds_write_b128 v138, v[102:105] offset:53248
	s_waitcnt vmcnt(3)
	ds_write_b128 v138, v[106:109] offset:24576
	s_waitcnt vmcnt(2)
	ds_write_b128 v138, v[114:117] offset:57344
	s_waitcnt vmcnt(1)
	ds_write_b128 v138, v[118:121] offset:28672
	s_waitcnt vmcnt(0)
	ds_write_b128 v138, v[122:125] offset:61440
	s_waitcnt lgkmcnt(0)
	s_barrier
	s_cbranch_scc1 .LBB0_130
	v_add_co_u32_e32 v82, vcc, 0x2360000, v136
	s_nop 1
	v_addc_co_u32_e32 v83, vcc, 0, v137, vcc
	v_add_co_u32_e32 v86, vcc, 0xbc0000, v134
	global_load_dwordx4 v[82:85], v[82:83], off offset:384
	s_nop 0
	v_addc_co_u32_e32 v87, vcc, 0, v135, vcc
	v_add_co_u32_e32 v94, vcc, 0x2370000, v136
	global_load_dwordx4 v[86:89], v[86:87], off offset:384
	s_nop 0
	v_addc_co_u32_e32 v95, vcc, 0, v137, vcc
	v_add_co_u32_e32 v102, vcc, 0xbd0000, v134
	global_load_dwordx4 v[94:97], v[94:95], off offset:384
	s_nop 0
	v_addc_co_u32_e32 v103, vcc, 0, v135, vcc
	v_add_co_u32_e32 v106, vcc, 0x2380000, v136
	global_load_dwordx4 v[102:105], v[102:103], off offset:384
	s_nop 0
	v_addc_co_u32_e32 v107, vcc, 0, v137, vcc
	v_add_co_u32_e32 v114, vcc, 0xbe0000, v134
	global_load_dwordx4 v[106:109], v[106:107], off offset:384
	s_nop 0
	v_addc_co_u32_e32 v115, vcc, 0, v135, vcc
	v_add_co_u32_e32 v118, vcc, 0x2390000, v136
	global_load_dwordx4 v[114:117], v[114:115], off offset:384
	s_nop 0
	v_addc_co_u32_e32 v119, vcc, 0, v137, vcc
	v_add_co_u32_e32 v122, vcc, 0xbf0000, v134
	global_load_dwordx4 v[118:121], v[118:119], off offset:384
	s_nop 0
	v_addc_co_u32_e32 v123, vcc, 0, v135, vcc
	global_load_dwordx4 v[122:125], v[122:123], off offset:384

; #define GLOAD(RA, RB, kt_) _Pragma("unroll") for (int i = 0; i < 4; ++i) { \
;     RA[i] = *(const u32x4*)(Ap + (size_t)(32 * i) * lda + (kt_) * 64); \
;     RB[i] = *(const u32x4*)(Bp + (size_t)(32 * i) * ldb + (kt_) * 64); }
; #define LSTORE(RA, RB, buf_) _Pragma("unroll") for (int i = 0; i < 4; ++i) { \
;     *(u32x4*)(smem + (buf_) * 16384 + woff + i * 4096) = RA[i]; \
;     *(u32x4*)(smem + 32768 + (buf_) * 16384 + woff + i * 4096) = RB[i]; }
; DI void gemm_kloop(f32x16 (&acc)[2][2], const u16* __restrict__ A, int lda, const u16* __restrict__ B, int ldb, int K,
;                    char* smem) {
;     ...
;   const int woff = lr * 128 + ((lc ^ ((lr >> 1) & 7)) << 4);
;   const int sw = (r >> 1) & 7;
;   const int aoff = (wr * 64 + r) * 128, boff = 32768 + (wc * 64 + r) * 128;
;   GLOAD(ra0, rb0, 0)
;   GLOAD(ra1, rb1, 1)
;   __syncthreads();
;   LSTORE(ra0, rb0, 0)
;   __syncthreads();
; #pragma unroll 1
;   for (int kt = 0; kt < nk; kt += 2) {
;     if (kt + 2 < nk) GLOAD(ra0, rb0, kt + 2)
;     COMPUTE(0)
;     LSTORE(ra1, rb1, 1)
;     __syncthreads();
;     if (kt + 3 < nk) GLOAD(ra1, rb1, kt + 3)
;     COMPUTE(1)
;     if (kt + 2 < nk) LSTORE(ra0, rb0, 0)
;     __syncthreads();
; DI void gemm_merge_phase(const Params& p, int mrows, int bid, int nb, char* smem) {
;     ...
;     gemm_kloop(a, YRW + (size_t)row0 * 512, 512, WT + WT_B + (size_t)col0 * 512, 512, 512, smem);
.LBB0_136:
	s_setprio 1
	v_add_u32_e32 v221, v216, v217
	ds_read_b128 v[230:233], v221
	v_add_u32_e32 v225, v215, v217
	ds_read_b128 v[234:237], v225 offset:32768
	ds_read_b128 v[238:241], v225 offset:36864
	v_add_u32_e32 v222, v216, v218
	v_add_u32_e32 v223, v216, v219
	v_add_u32_e32 v224, v216, v220
	ds_read_b128 v[248:251], v221 offset:4096
	ds_read_b128 v[252:255], v222
	s_waitcnt lgkmcnt(3)
	v_mfma_f32_32x32x16_bf16 v[50:65], v[230:233], v[234:237], v[50:65]
	s_waitcnt lgkmcnt(2)
	v_mfma_f32_32x32x16_bf16 v[34:49], v[230:233], v[238:241], v[34:49]
	v_add_u32_e32 v226, v215, v218
	ds_read_b128 v[230:233], v226 offset:32768
	s_waitcnt lgkmcnt(2)
	v_mfma_f32_32x32x16_bf16 v[18:33], v[248:251], v[234:237], v[18:33]
	ds_read_b128 v[234:237], v226 offset:36864
	s_waitcnt lgkmcnt(3)
	v_mfma_f32_32x32x16_bf16 v[2:17], v[248:251], v[238:241], v[2:17]
	v_add_u32_e32 v227, v215, v219
	ds_read_b128 v[248:251], v222 offset:4096
	ds_read_b128 v[238:241], v227 offset:32768
	s_waitcnt lgkmcnt(3)
	v_mfma_f32_32x32x16_bf16 v[50:65], v[252:255], v[230:233], v[50:65]
	s_waitcnt lgkmcnt(2)
	v_mfma_f32_32x32x16_bf16 v[34:49], v[252:255], v[234:237], v[34:49]
	ds_read_b128 v[252:255], v223
	s_waitcnt lgkmcnt(2)
	v_mfma_f32_32x32x16_bf16 v[18:33], v[248:251], v[230:233], v[18:33]
	ds_read_b128 v[230:233], v227 offset:36864
	s_waitcnt lgkmcnt(3)
	v_mfma_f32_32x32x16_bf16 v[2:17], v[248:251], v[234:237], v[2:17]
	ds_read_b128 v[248:251], v223 offset:4096
	ds_read_b128 v[234:237], v224
	s_waitcnt lgkmcnt(3)
	v_mfma_f32_32x32x16_bf16 v[50:65], v[252:255], v[238:241], v[50:65]
	s_waitcnt lgkmcnt(2)
	v_mfma_f32_32x32x16_bf16 v[34:49], v[252:255], v[230:233], v[34:49]
	v_add_u32_e32 v228, v215, v220
	ds_read_b128 v[252:255], v228 offset:32768
	s_waitcnt lgkmcnt(2)
	v_mfma_f32_32x32x16_bf16 v[18:33], v[248:251], v[238:241], v[18:33]
	ds_read_b128 v[238:241], v228 offset:36864
	s_waitcnt lgkmcnt(3)
	v_mfma_f32_32x32x16_bf16 v[2:17], v[248:251], v[230:233], v[2:17]
	ds_read_b128 v[248:251], v224 offset:4096
	s_waitcnt lgkmcnt(2)
	v_mfma_f32_32x32x16_bf16 v[50:65], v[234:237], v[252:255], v[50:65]
	s_waitcnt lgkmcnt(1)
	v_mfma_f32_32x32x16_bf16 v[34:49], v[234:237], v[238:241], v[34:49]
	s_waitcnt lgkmcnt(0)
	v_mfma_f32_32x32x16_bf16 v[18:33], v[248:251], v[252:255], v[18:33]
	s_waitcnt lgkmcnt(0)
	v_mfma_f32_32x32x16_bf16 v[2:17], v[248:251], v[238:241], v[2:17]
	s_setprio 0
	s_cmp_gt_u32 s7, 4
	s_waitcnt vmcnt(7)
	ds_write_b128 v214, v[94:97] offset:16384
	s_waitcnt vmcnt(6)
	ds_write_b128 v214, v[98:101] offset:49152
	s_waitcnt vmcnt(5)
	ds_write_b128 v214, v[102:105] offset:20480
	s_waitcnt vmcnt(4)
	ds_write_b128 v214, v[106:109] offset:53248
	s_waitcnt vmcnt(3)
	ds_write_b128 v214, v[114:117] offset:24576
	s_waitcnt vmcnt(2)
	ds_write_b128 v214, v[118:121] offset:57344
	s_waitcnt vmcnt(1)
	ds_write_b128 v214, v[122:125] offset:28672
	s_waitcnt vmcnt(0)
	ds_write_b128 v214, v[126:129] offset:61440
	s_waitcnt lgkmcnt(0)
	s_barrier
	s_cbranch_scc1 .LBB0_138
	v_add_co_u32_e32 v94, vcc, 0xb360000, v136
	s_nop 1
	v_addc_co_u32_e32 v95, vcc, 0, v137, vcc
	v_add_co_u32_e32 v98, vcc, 0xfc0000, v134
	global_load_dwordx4 v[94:97], v[94:95], off offset:384
	s_nop 0
	v_addc_co_u32_e32 v99, vcc, 0, v135, vcc
	v_add_co_u32_e32 v102, vcc, 0xb368000, v136
	global_load_dwordx4 v[98:101], v[98:99], off offset:384
	s_nop 0
	v_addc_co_u32_e32 v103, vcc, 0, v137, vcc
	v_add_co_u32_e32 v106, vcc, 0xfc8000, v134
	global_load_dwordx4 v[102:105], v[102:103], off offset:384
	s_nop 0
	v_addc_co_u32_e32 v107, vcc, 0, v135, vcc
	v_add_co_u32_e32 v114, vcc, 0xb370000, v136
	global_load_dwordx4 v[106:109], v[106:107], off offset:384
	s_nop 0
	v_addc_co_u32_e32 v115, vcc, 0, v137, vcc
	v_add_co_u32_e32 v118, vcc, 0xfd0000, v134
	global_load_dwordx4 v[114:117], v[114:115], off offset:384
	s_nop 0
	v_addc_co_u32_e32 v119, vcc, 0, v135, vcc
	v_add_co_u32_e32 v122, vcc, 0xb378000, v136
	global_load_dwordx4 v[118:121], v[118:119], off offset:384
	s_nop 0
	v_addc_co_u32_e32 v123, vcc, 0, v137, vcc
	v_add_co_u32_e32 v126, vcc, 0xfd8000, v134
	global_load_dwordx4 v[122:125], v[122:123], off offset:384
	s_nop 0
	v_addc_co_u32_e32 v127, vcc, 0, v135, vcc
	global_load_dwordx4 v[126:129], v[126:127], off offset:384

; #define MFMA32(a, b, c) __builtin_amdgcn_mfma_f32_32x32x16_bf16((a), (b), (c), 0, 0, 0)
; DI void gemm_kloop4(f32x16 (&acc)[4][2], const u16* __restrict__ A, int lda, const u16* __restrict__ B, int ldb, int K,
;                     char* smem) {
;     ...
;     __builtin_amdgcn_s_setprio(1);
; #pragma unroll
;     for (int s = 0; s < 4; ++s) {
;       const int ch = ((2 * s + h5) ^ sw) << 4;
;       const bf16x8 b0 = *(const bf16x8*)(smem + boff + ch);
;       const bf16x8 b1 = *(const bf16x8*)(smem + boff + 4096 + ch);
; #pragma unroll
;       for (int mt = 0; mt < 4; ++mt) {
;         const bf16x8 a = *(const bf16x8*)(smem + aoff + mt * 4096 + ch);
;         acc[mt][0] = MFMA32(a, b0, acc[mt][0]);
;         acc[mt][1] = MFMA32(a, b1, acc[mt][1]);
;       }
;     }
;     __builtin_amdgcn_s_setprio(0);
;     __syncthreads();
;     if (kt + 1 < nk) {
; #pragma unroll
;       for (int i = 0; i < 8; ++i) *(u32x4*)(smem + woff + i * 4096) = ra[i];
; #pragma unroll
;       for (int i = 0; i < 4; ++i) *(u32x4*)(smem + 32768 + woff + i * 4096) = rb[i];
;     }
;     __syncthreads();
.LBB0_509:
	s_setprio 1
	v_add_u32_e32 v189, v179, v185
	ds_read_b128 v[208:211], v189 offset:32768
	ds_read_b128 v[212:215], v189 offset:36864
	v_add_u32_e32 v189, v184, v185
	ds_read_b128 v[216:219], v189
	ds_read_b128 v[220:223], v189 offset:4096
	ds_read_b128 v[224:227], v189 offset:8192
	ds_read_b128 v[228:231], v189 offset:12288
	v_add_u32_e32 v189, v179, v186
	ds_read_b128 v[232:235], v189 offset:32768
	ds_read_b128 v[236:239], v189 offset:36864
	v_add_u32_e32 v189, v184, v186
	ds_read_b128 v[248:251], v189
	ds_read_b128 v[252:255], v189 offset:4096
	s_waitcnt lgkmcnt(7)
	v_mfma_f32_32x32x16_bf16 v[114:129], v[216:219], v[208:211], v[114:129]
	s_waitcnt lgkmcnt(7)
	v_mfma_f32_32x32x16_bf16 v[98:113], v[216:219], v[212:215], v[98:113]
	ds_read_b128 v[216:219], v189 offset:8192
	s_waitcnt lgkmcnt(7)
	v_mfma_f32_32x32x16_bf16 v[82:97], v[220:223], v[208:211], v[82:97]
	s_waitcnt lgkmcnt(7)
	v_mfma_f32_32x32x16_bf16 v[66:81], v[220:223], v[212:215], v[66:81]
	ds_read_b128 v[220:223], v189 offset:12288
	s_waitcnt lgkmcnt(7)
	v_mfma_f32_32x32x16_bf16 v[50:65], v[224:227], v[208:211], v[50:65]
	s_waitcnt lgkmcnt(7)
	v_mfma_f32_32x32x16_bf16 v[34:49], v[224:227], v[212:215], v[34:49]
	v_add_u32_e32 v189, v179, v187
	ds_read_b128 v[224:227], v189 offset:32768
	s_waitcnt lgkmcnt(7)
	v_mfma_f32_32x32x16_bf16 v[18:33], v[228:231], v[208:211], v[18:33]
	ds_read_b128 v[208:211], v189 offset:36864
	s_waitcnt lgkmcnt(8)
	v_mfma_f32_32x32x16_bf16 v[2:17], v[228:231], v[212:215], v[2:17]
	v_add_u32_e32 v189, v184, v187
	ds_read_b128 v[228:231], v189
	ds_read_b128 v[212:215], v189 offset:4096
	s_waitcnt lgkmcnt(7)
	v_mfma_f32_32x32x16_bf16 v[114:129], v[248:251], v[232:235], v[114:129]
	s_waitcnt lgkmcnt(7)
	v_mfma_f32_32x32x16_bf16 v[98:113], v[248:251], v[236:239], v[98:113]
	ds_read_b128 v[248:251], v189 offset:8192
	s_waitcnt lgkmcnt(7)
	v_mfma_f32_32x32x16_bf16 v[82:97], v[252:255], v[232:235], v[82:97]
	s_waitcnt lgkmcnt(7)
	v_mfma_f32_32x32x16_bf16 v[66:81], v[252:255], v[236:239], v[66:81]
	ds_read_b128 v[252:255], v189 offset:12288
	s_waitcnt lgkmcnt(7)
	v_mfma_f32_32x32x16_bf16 v[50:65], v[216:219], v[232:235], v[50:65]
	s_waitcnt lgkmcnt(7)
	v_mfma_f32_32x32x16_bf16 v[34:49], v[216:219], v[236:239], v[34:49]
	v_add_u32_e32 v189, v179, v188
	ds_read_b128 v[216:219], v189 offset:32768
	s_waitcnt lgkmcnt(7)
	v_mfma_f32_32x32x16_bf16 v[18:33], v[220:223], v[232:235], v[18:33]
	ds_read_b128 v[232:235], v189 offset:36864
	s_waitcnt lgkmcnt(8)
	v_mfma_f32_32x32x16_bf16 v[2:17], v[220:223], v[236:239], v[2:17]
	v_add_u32_e32 v189, v184, v188
	ds_read_b128 v[220:223], v189
	ds_read_b128 v[236:239], v189 offset:4096
	s_waitcnt lgkmcnt(7)
	v_mfma_f32_32x32x16_bf16 v[114:129], v[228:231], v[224:227], v[114:129]
	s_waitcnt lgkmcnt(7)
	v_mfma_f32_32x32x16_bf16 v[98:113], v[228:231], v[208:211], v[98:113]
	ds_read_b128 v[228:231], v189 offset:8192
	s_waitcnt lgkmcnt(7)
	v_mfma_f32_32x32x16_bf16 v[82:97], v[212:215], v[224:227], v[82:97]
	s_waitcnt lgkmcnt(7)
	v_mfma_f32_32x32x16_bf16 v[66:81], v[212:215], v[208:211], v[66:81]
	ds_read_b128 v[212:215], v189 offset:12288
	s_waitcnt lgkmcnt(7)
	v_mfma_f32_32x32x16_bf16 v[50:65], v[248:251], v[224:227], v[50:65]
	s_waitcnt lgkmcnt(7)
	v_mfma_f32_32x32x16_bf16 v[34:49], v[248:251], v[208:211], v[34:49]
	s_waitcnt lgkmcnt(6)
	v_mfma_f32_32x32x16_bf16 v[18:33], v[252:255], v[224:227], v[18:33]
	s_waitcnt lgkmcnt(6)
	v_mfma_f32_32x32x16_bf16 v[2:17], v[252:255], v[208:211], v[2:17]
	s_waitcnt lgkmcnt(3)
	v_mfma_f32_32x32x16_bf16 v[114:129], v[220:223], v[216:219], v[114:129]
	s_waitcnt lgkmcnt(3)
	v_mfma_f32_32x32x16_bf16 v[98:113], v[220:223], v[232:235], v[98:113]
	s_waitcnt lgkmcnt(2)
	v_mfma_f32_32x32x16_bf16 v[82:97], v[236:239], v[216:219], v[82:97]
	s_waitcnt lgkmcnt(2)
	v_mfma_f32_32x32x16_bf16 v[66:81], v[236:239], v[232:235], v[66:81]
	s_waitcnt lgkmcnt(1)
	v_mfma_f32_32x32x16_bf16 v[50:65], v[228:231], v[216:219], v[50:65]
	s_waitcnt lgkmcnt(1)
	v_mfma_f32_32x32x16_bf16 v[34:49], v[228:231], v[232:235], v[34:49]
	s_waitcnt lgkmcnt(0)
	v_mfma_f32_32x32x16_bf16 v[18:33], v[212:215], v[216:219], v[18:33]
	s_waitcnt lgkmcnt(0)
	v_mfma_f32_32x32x16_bf16 v[2:17], v[212:215], v[232:235], v[2:17]
	s_setprio 0
	s_andn2_b64 vcc, exec, s[40:41]
	s_barrier
	s_cbranch_vccnz .LBB0_506
	s_waitcnt vmcnt(11)
	ds_write_b128 v0, v[142:145]
	s_waitcnt vmcnt(10)
	ds_write_b128 v0, v[130:133] offset:4096
	s_waitcnt vmcnt(9)
	ds_write_b128 v0, v[134:137] offset:8192
	s_waitcnt vmcnt(8)
	ds_write_b128 v0, v[138:141] offset:12288
	s_waitcnt vmcnt(7)
	ds_write_b128 v0, v[146:149] offset:16384
	s_waitcnt vmcnt(6)
	ds_write_b128 v0, v[150:153] offset:20480
	s_waitcnt vmcnt(5)
	ds_write_b128 v0, v[154:157] offset:24576
	s_waitcnt vmcnt(4)
	ds_write_b128 v0, v[158:161] offset:28672
	s_waitcnt vmcnt(3)
	ds_write_b128 v0, v[162:165] offset:32768
	s_waitcnt vmcnt(2)
	ds_write_b128 v0, v[166:169] offset:36864
	s_waitcnt vmcnt(1)
	ds_write_b128 v0, v[170:173] offset:40960
	s_waitcnt vmcnt(0)
	ds_write_b128 v0, v[174:177] offset:45056
	s_branch .LBB0_506
